# slot pass parameters computed from gridDim at the end of the prologue pass (no load in front of the grid barrier)
# baseline (speedup 1.0000x reference)
; #define LAS __attribute__((address_space(3)))
; DI int ltid(int wv) { asm volatile("" : "+s"(wv)); int l = __builtin_amdgcn_mbcnt_hi(~0u, __builtin_amdgcn_mbcnt_lo(~0u, 0u)); asm volatile("" : "+v"(l)); return wv * 64 + l; }
; DI void phase_prologue(int wv, const ArgP a, LAS unsigned char* lds, int parts) {
;     unsigned char* ws = a.ws();
;     const int tid = ltid(wv), wave = tid >> 6, lane = tid & 63;
;     LAS float* scr = (LAS float*)(lds + wave * 8448);
;     const int gw = blockIdx.x * 8 + wave, NGW = gridDim.x * 8; int cum = 0;
;     if (parts & 1) {
;     { FW1 f{a.in(3), a.in(2)}; tr_items(f, 1024, 1536, (bf16_t*)(ws + O_W1T), scr, gw, NGW, lane, cum); }
.Lpro_entry:
	s_cmp_eq_u32 s90, 0
	s_cselect_b64 s[94:95], -1, 0
	s_cselect_b64 s[96:97], 0, -1
	v_mbcnt_lo_u32_b32 v0, -1, 0
	s_lshr_b32 s50, s48, 6
	v_mbcnt_hi_u32_b32 v192, -1, v0
	s_mov_b64 s[2:3], s[82:83]
	s_mov_b32 s0, s50
	v_mov_b32_e32 v14, v192
	s_load_dwordx2 s[12:13], s[2:3], 0xe8
	s_load_dword s24, s[82:83], 0xf8
	s_lshl_b32 s46, s80, 3
	s_sub_i32 s46, s46, s91
	s_add_u32 s88, s82, 0xf8
	s_addc_u32 s89, s83, 0
	v_lshl_add_u32 v15, s0, 6, v14
	s_waitcnt lgkmcnt(0)
	s_lshl_b32 s14, s24, 3
	s_cmp_eq_u32 s90, 1
	s_cselect_b32 s14, s99, s14
	s_abs_i32 s15, s14
	v_cvt_f32_u32_e32 v1, s15
	v_ashrrev_i32_e32 v0, 6, v15
	s_movk_i32 s0, 0x2100
	v_mul_lo_u32 v2, v0, s0
	v_rcp_iflag_f32_e32 v3, v1
	v_add_u32_e32 v20, 0, v2
	s_sub_i32 s0, 0, s15
	v_add_u32_e32 v0, s46, v0
	v_mul_f32_e32 v2, 0x4f7ffffe, v3
	v_cvt_u32_f32_e32 v2, v2
	v_sub_u32_e32 v3, 0, v0
	v_max_i32_e32 v3, v0, v3
	v_ashrrev_i32_e32 v1, 31, v0
	v_readfirstlane_b32 s25, v2
	s_mul_i32 s0, s0, s25
	s_mul_hi_u32 s0, s25, s0
	s_add_i32 s25, s25, s0
	v_mul_hi_u32 v2, v3, s25
	v_mul_lo_u32 v2, v2, s15
	v_sub_u32_e32 v2, v3, v2
	v_subrev_u32_e32 v3, s15, v2
	v_cmp_le_u32_e32 vcc, s15, v2
	v_and_b32_e32 v16, 63, v14
	s_movk_i32 s0, 0x300
	v_cndmask_b32_e32 v2, v2, v3, vcc
	v_subrev_u32_e32 v3, s15, v2
	v_cmp_le_u32_e32 vcc, s15, v2
	s_mul_hi_u32 s16, s25, 0x300
	v_and_b32_e32 v18, 31, v14
	v_cndmask_b32_e32 v2, v2, v3, vcc
	v_xor_b32_e32 v2, v2, v1
	v_sub_u32_e32 v2, v2, v1
	v_ashrrev_i32_e32 v3, 31, v2
	v_and_b32_e32 v3, s14, v3
	v_add_u32_e32 v10, v3, v2
	v_cmp_gt_i32_e32 vcc, s0, v10
	v_lshrrev_b32_e32 v17, 5, v16
	v_lshrrev_b32_e32 v19, 3, v16
	v_lshlrev_b32_e32 v21, 3, v16
	s_and_b64 vcc, vcc, s[94:95]
	s_and_saveexec_b64 s[0:1], vcc
	s_cbranch_execz .LBB0_82
	s_load_dwordx4 s[4:7], s[2:3], 0x10
	v_lshrrev_b32_e32 v13, 3, v16
	v_and_b32_e32 v2, 56, v21
	v_and_b32_e32 v11, 31, v14
	v_lshrrev_b32_e32 v12, 5, v16
	v_mul_u32_u24_e32 v5, 0x84, v2
	v_lshlrev_b32_e32 v2, 1, v2
	v_mov_b32_e32 v3, 0
	v_lshlrev_b32_e32 v6, 2, v13
	v_lshl_add_u32 v4, v11, 2, v20
	v_lshl_add_u64 v[2:3], s[12:13], 0, v[2:3]
	s_mov_b64 s[8:9], 0x3e0b000
	v_add3_u32 v22, v20, v5, v6
	v_mul_u32_u24_e32 v5, 0x84, v12
	v_lshl_add_u64 v[2:3], v[2:3], 0, s[8:9]
	v_lshlrev_b32_e32 v23, 5, v10
	s_lshl_b32 s17, s14, 5
	s_mov_b64 s[8:9], 0
	s_mov_b32 s18, 0x2aaaaaab
	s_movk_i32 s19, 0xfa00
	s_movk_i32 s20, 0x5a0
	s_movk_i32 s21, 0x1680
	v_add_u32_e32 v24, v4, v5
	s_movk_i32 s22, 0x2ff
	s_branch .LBB0_18

; #define LAS __attribute__((address_space(3)))
; DI int ltid(int wv) { asm volatile("" : "+s"(wv)); int l = __builtin_amdgcn_mbcnt_hi(~0u, __builtin_amdgcn_mbcnt_lo(~0u, 0u)); asm volatile("" : "+v"(l)); return wv * 64 + l; }
; DI unsigned xb_xcc_id() { return (unsigned)__builtin_amdgcn_s_getreg((3 << 11) | 20) & 0xFu; }
; DI void xcd_barrier(int wv, unsigned* bar, volatile LAS unsigned* st) {
;     asm volatile("s_waitcnt vmcnt(0)" ::: "memory");
;     __syncthreads();
;     if (ltid(wv) == 0) {
;         const unsigned x = xb_xcc_id();
;         __builtin_amdgcn_s_waitcnt(0);
;         unsigned nloc = st[0], nx = st[1];
;         if (nloc == 0u) { xcd_barrier_complete(bar, x, nloc, nx); st[0] = nloc; st[1] = nx; }
.LBB0_316:
	s_or_b64 exec, exec, s[0:1]
	s_movk_i32 s98, 0x180
.Lslot_mod:
	s_cmp_ge_u32 s98, s24
	s_cbranch_scc0 .Lslot_mod_done
	s_sub_u32 s98, s98, s24
	s_branch .Lslot_mod
.Lslot_mod_done:
	s_sub_u32 s99, s24, s98
	s_lshl_b32 s99, s99, 3
	s_cmp_eq_u32 s90, 1
	s_cbranch_scc1 .Lslot_return
	s_mov_b64 s[2:3], s[82:83]
	s_mov_b32 s0, s50
	s_waitcnt vmcnt(0)
	s_waitcnt lgkmcnt(0)
	s_barrier
	s_lshl_b32 s0, s0, 6
	v_mov_b32_e32 v0, v192
	s_sub_i32 s0, 0, s0
	s_nop 0
	v_cmp_eq_u32_e32 vcc, s0, v0
	s_and_saveexec_b64 s[0:1], vcc
	s_xor_b64 s[0:1], exec, s[0:1]
	v_writelane_b32 v240, s50, 0
	s_cbranch_execz .LBB0_369
	s_add_i32 s5, 0, 0x22000
	v_mov_b32_e32 v0, s5
	s_load_dwordx2 s[2:3], s[2:3], 0xe8
	s_getreg_b32 s4, hwreg(HW_REG_XCC_ID, 0, 4)
	s_waitcnt vmcnt(0) expcnt(0) lgkmcnt(0)
	ds_read_b32 v2, v0
	s_add_i32 s5, 0, 0x22004
	v_mov_b32_e32 v0, s5
	ds_read_b32 v0, v0
	s_and_b32 s47, s4, 15
	s_waitcnt lgkmcnt(1)
	v_cmp_ne_u32_e32 vcc, 0, v2
	s_cbranch_vccnz .LBB0_332
	s_add_u32 s4, s2, 0x1d83200
	s_addc_u32 s5, s3, 0
	s_add_u32 s6, s2, 0x1d83400
	s_addc_u32 s7, s3, 0
	s_add_u32 s8, s2, 0x1d83500
	s_addc_u32 s9, s3, 0
	s_add_u32 s10, s2, 0x1d83600
	s_addc_u32 s11, s3, 0
	s_add_u32 s12, s2, 0x1d83700
	s_addc_u32 s13, s3, 0
	s_add_u32 s14, s2, 0x1d83800
	s_addc_u32 s15, s3, 0
	s_add_u32 s16, s2, 0x1d83900
	s_addc_u32 s17, s3, 0
	s_add_u32 s18, s2, 0x1d83a00
	s_addc_u32 s19, s3, 0
	s_add_u32 s20, s2, 0x1d83b00
	s_addc_u32 s21, s3, 0
	s_add_u32 s22, s2, 0x1d83c00
	s_addc_u32 s23, s3, 0
	s_add_u32 s24, s2, 0x1d83d00
	s_addc_u32 s25, s3, 0
	s_add_u32 s26, s2, 0x1d83e00
	s_addc_u32 s27, s3, 0
	s_add_u32 s28, s2, 0x1d83f00
	s_addc_u32 s29, s3, 0
	s_add_u32 s30, s2, 0x1d84000
	s_addc_u32 s31, s3, 0
	s_add_u32 s34, s2, 0x1d84100
	s_load_dword s49, s[88:89], 0x0
	s_addc_u32 s35, s3, 0
	s_add_u32 s36, s2, 0x1d84200
	s_addc_u32 s37, s3, 0
	s_add_u32 s38, s2, 0x1d84300
	s_addc_u32 s39, s3, 0
	s_mov_b32 s50, 1
	v_mov_b32_e32 v16, 0
	s_branch .LBB0_320

; #define WSB (getargs().ws())
; #define GSYNC() xcd_barrier(wv, BARW, BARST)
; __global__ void __launch_bounds__(512, 2) fwd_kernel(Args a_unused) {
;     ...
;       pg8::gemm_phase<false>(wv, lds, XBP, 1024, (const bf16_t*)(WSB + O_W1T), 1024, 1024, 64, 6, E); }
;     }
;     ...
;     GSYNC();
.LBB0_388:
	s_cmp_lt_u32 s80, s98
	s_cbranch_scc1 .Lslot_skip
	s_lshl_b32 s91, s98, 3
	s_barrier
	s_mov_b32 s90, 1
	s_branch .Lpro_entry
